# consumer waves raised to s_setprio 3 during the scan chunk loop
# baseline (speedup 1.0000x reference)
; #define LAS __attribute__((address_space(3)))
; template <int CTRL> __device__ __forceinline__ float dpp_f(float x) { return __int_as_float(__builtin_amdgcn_update_dpp(0, __float_as_int(x), CTRL, 0xf, 0xf, false)); }
; __device__ __forceinline__ void p8_scan(const Args& a, LAS unsigned char* lds) {
;     ...
;             f32x2 S01 = (f32x2){0.f, 0.f}, S23 = (f32x2){0.f, 0.f};
;             const bool holds_y = (lane & 3) == 0;
;             const float m0 = (lane & 15) == 0 ? 1.0f : 0.0f;
;             __syncthreads();
;             for (int c = 0; c < T / TC; ++c) {
;                 const int cur = c & 1;
;                 const LAS float* bt = buf + cur * TC * SPITCH;
;                 LAS float* yd = holds_y ? (ybuf + cur * TC * 64 + 4 * (4 * w + (lane >> 4)) + ((lane & 15) >> 2)) : (dump + lane);
;                 ScanOps o; scan_ld(o, bt, jq4, myrow);
; #pragma unroll 16
;                 for (int tt = 0; tt < TC; ++tt) {
;                     ScanOps n; scan_ld(n, bt + (tt + 1 < TC ? tt + 1 : tt) * SPITCH, jq4, myrow);
;                     __builtin_amdgcn_sched_barrier(0);
;                     f32x2 ta = S01 * o.al.lo, ty = S01 * o.wr.lo; ta = S23 * o.al.hi + ta; ty = S23 * o.wr.hi + ty;
;                     float pa = ta.x + ta.y, py = ty.x + ty.y;
;                     f32x2 kv01 = o.kv.lo * o.vi, kv23 = o.kv.hi * o.vi;
;     ...
;                     asm volatile("" : "+v"(kv01), "+v"(kv23), "+v"(vc));
;                     pa += dpp_f<0x121>(pa); py += dpp_f<0x121>(py); pa += dpp_f<0x122>(pa); py += dpp_f<0x122>(py);
;                     pa += dpp_f<0x124>(pa); pa += dpp_f<0x128>(pa);
;                     S01 = S01 * o.wv.lo + (o.be.lo * pa + kv01);
;                     S23 = S23 * o.wv.hi + (o.be.hi * pa + kv23);
;     ...
;                     __builtin_amdgcn_sched_barrier(0);
;                     o = n;
;                 }
.LBB0_1088:
	s_ashr_i32 s14, s71, 2
	s_and_b32 s42, s14, -16
	s_and_b64 vcc, exec, s[16:17]
	s_mov_b64 s[44:45], -1
	s_barrier
	s_cbranch_vccz .LBB0_1094
	s_setprio 3
	s_lshl_b32 s14, s14, 2
	s_andn2_b32 s14, s14, 63
	v_mov_b32_e32 v28, v29
	v_or_b32_e32 v1, s42, v121
	s_waitcnt vmcnt(15)
	v_add_u32_e32 v34, s14, v133
	s_mov_b32 s14, 0
	s_mov_b64 s[44:45], 0
	v_mov_b64_e32 v[22:23], v[28:29]
	v_mov_b64_e32 v[24:25], v[28:29]
	s_barrier
.LBB0_1090:
	s_and_b32 s43, s14, 1
	s_mul_i32 s52, s43, 0xc400
	s_lshl_b32 s43, s43, 13
	v_lshl_add_u32 v38, v27, 2, s52
	v_lshl_add_u32 v39, v1, 2, s52
	v_mov_b32_e32 v40, s52
	v_add_u32_e32 v41, s43, v123
	v_cndmask_b32_e64 v41, v124, v41, s[2:3]
	ds_read_b128 v[10:13], v38 offset:512
	ds_read_b128 v[18:21], v38 offset:1024
	ds_read_b128 v[6:9], v38 offset:256
	ds_read_b32 v28, v39 offset:1280
	ds_read_b128 v[2:5], v38 offset:0
	ds_read_b32 v33, v40 offset:1540
	ds_read_b128 v[14:17], v38 offset:768
	s_waitcnt lgkmcnt(3)
	ds_read_b128 v[50:53], v38 offset:2080
	ds_read_b128 v[58:61], v38 offset:2592
	ds_read_b128 v[46:49], v38 offset:1824
	ds_read_b32 v62, v39 offset:2848
	ds_read_b128 v[42:45], v38 offset:1568
	ds_read_b32 v65, v40 offset:3108
	ds_read_b128 v[54:57], v38 offset:2336
	v_pk_mul_f32 v[34:35], v[22:23], v[10:11]
	v_pk_mul_f32 v[36:37], v[22:23], v[18:19]
	v_pk_fma_f32 v[34:35], v[24:25], v[12:13], v[34:35]
	v_pk_fma_f32 v[36:37], v[24:25], v[20:21], v[36:37]
	v_add_f32_e32 v34, v34, v35
	v_add_f32_e32 v36, v36, v37
	v_pk_mul_f32 v[6:7], v[6:7], v[28:29] op_sel_hi:[1,0]
	v_add_f32_dpp v34, v34, v34 row_ror:1 row_mask:0xf bank_mask:0xf bound_ctrl:1
	v_pk_mul_f32 v[8:9], v[8:9], v[28:29] op_sel_hi:[1,0]
	v_add_f32_dpp v36, v36, v36 row_ror:1 row_mask:0xf bank_mask:0xf bound_ctrl:1
	v_add_f32_dpp v34, v34, v34 row_ror:2 row_mask:0xf bank_mask:0xf bound_ctrl:1
	s_waitcnt lgkmcnt(7)
	v_pk_fma_f32 v[6:7], v[22:23], v[2:3], v[6:7]
	v_add_f32_dpp v36, v36, v36 row_ror:2 row_mask:0xf bank_mask:0xf bound_ctrl:1
	v_add_f32_dpp v34, v34, v34 row_ror:4 row_mask:0xf bank_mask:0xf bound_ctrl:1
	v_pk_fma_f32 v[8:9], v[24:25], v[4:5], v[8:9]
	v_fmac_f32_e32 v36, v28, v33
	v_add_f32_dpp v34, v34, v34 row_ror:8 row_mask:0xf bank_mask:0xf bound_ctrl:1
	v_pk_fma_f32 v[22:23], v[14:15], v[34:35], v[6:7] op_sel_hi:[1,0,1]
	v_pk_fma_f32 v[24:25], v[16:17], v[34:35], v[8:9] op_sel_hi:[1,0,1]
	s_waitcnt lgkmcnt(3)
	ds_read_b128 v[10:13], v38 offset:3648
	ds_read_b128 v[18:21], v38 offset:4160
	ds_read_b128 v[6:9], v38 offset:3392
	ds_read_b32 v28, v39 offset:4416
	ds_read_b128 v[2:5], v38 offset:3136
	ds_read_b32 v33, v40 offset:4676
	ds_read_b128 v[14:17], v38 offset:3904
	v_pk_mul_f32 v[34:35], v[22:23], v[50:51]
	v_pk_mul_f32 v[66:67], v[22:23], v[58:59]
	v_pk_fma_f32 v[34:35], v[24:25], v[52:53], v[34:35]
	v_pk_fma_f32 v[66:67], v[24:25], v[60:61], v[66:67]
	v_add_f32_e32 v34, v34, v35
	v_add_f32_e32 v66, v66, v67
	v_pk_mul_f32 v[46:47], v[46:47], v[62:63] op_sel_hi:[1,0]
	v_add_f32_dpp v34, v34, v34 row_ror:1 row_mask:0xf bank_mask:0xf bound_ctrl:1
	v_pk_mul_f32 v[48:49], v[48:49], v[62:63] op_sel_hi:[1,0]
	v_add_f32_dpp v66, v66, v66 row_ror:1 row_mask:0xf bank_mask:0xf bound_ctrl:1
	v_add_f32_dpp v34, v34, v34 row_ror:2 row_mask:0xf bank_mask:0xf bound_ctrl:1
	s_waitcnt lgkmcnt(7)
	v_pk_fma_f32 v[46:47], v[22:23], v[42:43], v[46:47]
	v_add_f32_dpp v66, v66, v66 row_ror:2 row_mask:0xf bank_mask:0xf bound_ctrl:1
	v_add_f32_dpp v34, v34, v34 row_ror:4 row_mask:0xf bank_mask:0xf bound_ctrl:1
	v_pk_fma_f32 v[48:49], v[24:25], v[44:45], v[48:49]
	v_fmac_f32_e32 v66, v62, v65
	v_add_f32_dpp v34, v34, v34 row_ror:8 row_mask:0xf bank_mask:0xf bound_ctrl:1
	v_pk_fma_f32 v[22:23], v[54:55], v[34:35], v[46:47] op_sel_hi:[1,0,1]
	v_pk_fma_f32 v[24:25], v[56:57], v[34:35], v[48:49] op_sel_hi:[1,0,1]
	ds_write2st64_b32 v41, v36, v66 offset0:0 offset1:1
	s_waitcnt lgkmcnt(4)
	ds_read_b128 v[50:53], v38 offset:5216
	ds_read_b128 v[58:61], v38 offset:5728
	ds_read_b128 v[46:49], v38 offset:4960
	ds_read_b32 v62, v39 offset:5984
	ds_read_b128 v[42:45], v38 offset:4704
	ds_read_b32 v65, v40 offset:6244
	ds_read_b128 v[54:57], v38 offset:5472
	v_pk_mul_f32 v[34:35], v[22:23], v[10:11]
	v_pk_mul_f32 v[36:37], v[22:23], v[18:19]
	v_pk_fma_f32 v[34:35], v[24:25], v[12:13], v[34:35]
	v_pk_fma_f32 v[36:37], v[24:25], v[20:21], v[36:37]
	v_add_f32_e32 v34, v34, v35
	v_add_f32_e32 v36, v36, v37
	v_pk_mul_f32 v[6:7], v[6:7], v[28:29] op_sel_hi:[1,0]
	v_add_f32_dpp v34, v34, v34 row_ror:1 row_mask:0xf bank_mask:0xf bound_ctrl:1
	v_pk_mul_f32 v[8:9], v[8:9], v[28:29] op_sel_hi:[1,0]
	v_add_f32_dpp v36, v36, v36 row_ror:1 row_mask:0xf bank_mask:0xf bound_ctrl:1
	v_add_f32_dpp v34, v34, v34 row_ror:2 row_mask:0xf bank_mask:0xf bound_ctrl:1
	s_waitcnt lgkmcnt(8)
	v_pk_fma_f32 v[6:7], v[22:23], v[2:3], v[6:7]
	v_add_f32_dpp v36, v36, v36 row_ror:2 row_mask:0xf bank_mask:0xf bound_ctrl:1
	v_add_f32_dpp v34, v34, v34 row_ror:4 row_mask:0xf bank_mask:0xf bound_ctrl:1
	v_pk_fma_f32 v[8:9], v[24:25], v[4:5], v[8:9]
	v_fmac_f32_e32 v36, v28, v33
	v_add_f32_dpp v34, v34, v34 row_ror:8 row_mask:0xf bank_mask:0xf bound_ctrl:1
	v_pk_fma_f32 v[22:23], v[14:15], v[34:35], v[6:7] op_sel_hi:[1,0,1]
	v_pk_fma_f32 v[24:25], v[16:17], v[34:35], v[8:9] op_sel_hi:[1,0,1]
	s_waitcnt lgkmcnt(3)
; template <int CTRL> __device__ __forceinline__ float dpp_f(float x) { return __int_as_float(__builtin_amdgcn_update_dpp(0, __float_as_int(x), CTRL, 0xf, 0xf, false)); }
; __device__ __forceinline__ void p8_scan(const Args& a, LAS unsigned char* lds) {
;     ...
;                 for (int tt = 0; tt < TC; ++tt) {
;                     ScanOps n; scan_ld(n, bt + (tt + 1 < TC ? tt + 1 : tt) * SPITCH, jq4, myrow);
;                     __builtin_amdgcn_sched_barrier(0);
;                     f32x2 ta = S01 * o.al.lo, ty = S01 * o.wr.lo; ta = S23 * o.al.hi + ta; ty = S23 * o.wr.hi + ty;
;                     float pa = ta.x + ta.y, py = ty.x + ty.y;
;                     f32x2 kv01 = o.kv.lo * o.vi, kv23 = o.kv.hi * o.vi;
;     ...
;                     asm volatile("" : "+v"(kv01), "+v"(kv23), "+v"(vc));
;                     pa += dpp_f<0x121>(pa); py += dpp_f<0x121>(py); pa += dpp_f<0x122>(pa); py += dpp_f<0x122>(py);
;                     pa += dpp_f<0x124>(pa); pa += dpp_f<0x128>(pa);
;                     S01 = S01 * o.wv.lo + (o.be.lo * pa + kv01);
;                     S23 = S23 * o.wv.hi + (o.be.hi * pa + kv23);
;     ...
;                     __builtin_amdgcn_sched_barrier(0);
;                     o = n;
	ds_read_b128 v[10:13], v38 offset:6784
	ds_read_b128 v[18:21], v38 offset:7296
	ds_read_b128 v[6:9], v38 offset:6528
	ds_read_b32 v28, v39 offset:7552
	ds_read_b128 v[2:5], v38 offset:6272
	ds_read_b32 v33, v40 offset:7812
	ds_read_b128 v[14:17], v38 offset:7040
	v_pk_mul_f32 v[34:35], v[22:23], v[50:51]
	v_pk_mul_f32 v[66:67], v[22:23], v[58:59]
	v_pk_fma_f32 v[34:35], v[24:25], v[52:53], v[34:35]
	v_pk_fma_f32 v[66:67], v[24:25], v[60:61], v[66:67]
	v_add_f32_e32 v34, v34, v35
	v_add_f32_e32 v66, v66, v67
	v_pk_mul_f32 v[46:47], v[46:47], v[62:63] op_sel_hi:[1,0]
	v_add_f32_dpp v34, v34, v34 row_ror:1 row_mask:0xf bank_mask:0xf bound_ctrl:1
	v_pk_mul_f32 v[48:49], v[48:49], v[62:63] op_sel_hi:[1,0]
	v_add_f32_dpp v66, v66, v66 row_ror:1 row_mask:0xf bank_mask:0xf bound_ctrl:1
	v_add_f32_dpp v34, v34, v34 row_ror:2 row_mask:0xf bank_mask:0xf bound_ctrl:1
	s_waitcnt lgkmcnt(7)
	v_pk_fma_f32 v[46:47], v[22:23], v[42:43], v[46:47]
	v_add_f32_dpp v66, v66, v66 row_ror:2 row_mask:0xf bank_mask:0xf bound_ctrl:1
	v_add_f32_dpp v34, v34, v34 row_ror:4 row_mask:0xf bank_mask:0xf bound_ctrl:1
	v_pk_fma_f32 v[48:49], v[24:25], v[44:45], v[48:49]
	v_fmac_f32_e32 v66, v62, v65
	v_add_f32_dpp v34, v34, v34 row_ror:8 row_mask:0xf bank_mask:0xf bound_ctrl:1
	v_pk_fma_f32 v[22:23], v[54:55], v[34:35], v[46:47] op_sel_hi:[1,0,1]
	v_pk_fma_f32 v[24:25], v[56:57], v[34:35], v[48:49] op_sel_hi:[1,0,1]
	ds_write2st64_b32 v41, v36, v66 offset0:2 offset1:3
	s_waitcnt lgkmcnt(4)
	ds_read_b128 v[50:53], v38 offset:8352
	ds_read_b128 v[58:61], v38 offset:8864
	ds_read_b128 v[46:49], v38 offset:8096
	ds_read_b32 v62, v39 offset:9120
	ds_read_b128 v[42:45], v38 offset:7840
	ds_read_b32 v65, v40 offset:9380
	ds_read_b128 v[54:57], v38 offset:8608
	v_pk_mul_f32 v[34:35], v[22:23], v[10:11]
	v_pk_mul_f32 v[36:37], v[22:23], v[18:19]
	v_pk_fma_f32 v[34:35], v[24:25], v[12:13], v[34:35]
	v_pk_fma_f32 v[36:37], v[24:25], v[20:21], v[36:37]
	v_add_f32_e32 v34, v34, v35
	v_add_f32_e32 v36, v36, v37
	v_pk_mul_f32 v[6:7], v[6:7], v[28:29] op_sel_hi:[1,0]
	v_add_f32_dpp v34, v34, v34 row_ror:1 row_mask:0xf bank_mask:0xf bound_ctrl:1
	v_pk_mul_f32 v[8:9], v[8:9], v[28:29] op_sel_hi:[1,0]
	v_add_f32_dpp v36, v36, v36 row_ror:1 row_mask:0xf bank_mask:0xf bound_ctrl:1
	v_add_f32_dpp v34, v34, v34 row_ror:2 row_mask:0xf bank_mask:0xf bound_ctrl:1
	s_waitcnt lgkmcnt(8)
	v_pk_fma_f32 v[6:7], v[22:23], v[2:3], v[6:7]
	v_add_f32_dpp v36, v36, v36 row_ror:2 row_mask:0xf bank_mask:0xf bound_ctrl:1
	v_add_f32_dpp v34, v34, v34 row_ror:4 row_mask:0xf bank_mask:0xf bound_ctrl:1
	v_pk_fma_f32 v[8:9], v[24:25], v[4:5], v[8:9]
	v_fmac_f32_e32 v36, v28, v33
	v_add_f32_dpp v34, v34, v34 row_ror:8 row_mask:0xf bank_mask:0xf bound_ctrl:1
	v_pk_fma_f32 v[22:23], v[14:15], v[34:35], v[6:7] op_sel_hi:[1,0,1]
	v_pk_fma_f32 v[24:25], v[16:17], v[34:35], v[8:9] op_sel_hi:[1,0,1]
	s_waitcnt lgkmcnt(3)
	ds_read_b128 v[10:13], v38 offset:9920
	ds_read_b128 v[18:21], v38 offset:10432
	ds_read_b128 v[6:9], v38 offset:9664
	ds_read_b32 v28, v39 offset:10688
	ds_read_b128 v[2:5], v38 offset:9408
	ds_read_b32 v33, v40 offset:10948
	ds_read_b128 v[14:17], v38 offset:10176
	v_pk_mul_f32 v[34:35], v[22:23], v[50:51]
	v_pk_mul_f32 v[66:67], v[22:23], v[58:59]
	v_pk_fma_f32 v[34:35], v[24:25], v[52:53], v[34:35]
	v_pk_fma_f32 v[66:67], v[24:25], v[60:61], v[66:67]
	v_add_f32_e32 v34, v34, v35
	v_add_f32_e32 v66, v66, v67
	v_pk_mul_f32 v[46:47], v[46:47], v[62:63] op_sel_hi:[1,0]
	v_add_f32_dpp v34, v34, v34 row_ror:1 row_mask:0xf bank_mask:0xf bound_ctrl:1
	v_pk_mul_f32 v[48:49], v[48:49], v[62:63] op_sel_hi:[1,0]
	v_add_f32_dpp v66, v66, v66 row_ror:1 row_mask:0xf bank_mask:0xf bound_ctrl:1
	v_add_f32_dpp v34, v34, v34 row_ror:2 row_mask:0xf bank_mask:0xf bound_ctrl:1
	s_waitcnt lgkmcnt(7)
	v_pk_fma_f32 v[46:47], v[22:23], v[42:43], v[46:47]
	v_add_f32_dpp v66, v66, v66 row_ror:2 row_mask:0xf bank_mask:0xf bound_ctrl:1
	v_add_f32_dpp v34, v34, v34 row_ror:4 row_mask:0xf bank_mask:0xf bound_ctrl:1
	v_pk_fma_f32 v[48:49], v[24:25], v[44:45], v[48:49]
	v_fmac_f32_e32 v66, v62, v65
	v_add_f32_dpp v34, v34, v34 row_ror:8 row_mask:0xf bank_mask:0xf bound_ctrl:1
	v_pk_fma_f32 v[22:23], v[54:55], v[34:35], v[46:47] op_sel_hi:[1,0,1]
	v_pk_fma_f32 v[24:25], v[56:57], v[34:35], v[48:49] op_sel_hi:[1,0,1]
	ds_write2st64_b32 v41, v36, v66 offset0:4 offset1:5
	s_waitcnt lgkmcnt(4)
	ds_read_b128 v[50:53], v38 offset:11488
	ds_read_b128 v[58:61], v38 offset:12000
	ds_read_b128 v[46:49], v38 offset:11232
	ds_read_b32 v62, v39 offset:12256
	ds_read_b128 v[42:45], v38 offset:10976
	ds_read_b32 v65, v40 offset:12516
	ds_read_b128 v[54:57], v38 offset:11744
	v_pk_mul_f32 v[34:35], v[22:23], v[10:11]
	v_pk_mul_f32 v[36:37], v[22:23], v[18:19]
	v_pk_fma_f32 v[34:35], v[24:25], v[12:13], v[34:35]
	v_pk_fma_f32 v[36:37], v[24:25], v[20:21], v[36:37]
	v_add_f32_e32 v34, v34, v35
	v_add_f32_e32 v36, v36, v37
	v_pk_mul_f32 v[6:7], v[6:7], v[28:29] op_sel_hi:[1,0]
	v_add_f32_dpp v34, v34, v34 row_ror:1 row_mask:0xf bank_mask:0xf bound_ctrl:1
	v_pk_mul_f32 v[8:9], v[8:9], v[28:29] op_sel_hi:[1,0]
	v_add_f32_dpp v36, v36, v36 row_ror:1 row_mask:0xf bank_mask:0xf bound_ctrl:1
	v_add_f32_dpp v34, v34, v34 row_ror:2 row_mask:0xf bank_mask:0xf bound_ctrl:1
	s_waitcnt lgkmcnt(8)
	v_pk_fma_f32 v[6:7], v[22:23], v[2:3], v[6:7]
	v_add_f32_dpp v36, v36, v36 row_ror:2 row_mask:0xf bank_mask:0xf bound_ctrl:1
	v_add_f32_dpp v34, v34, v34 row_ror:4 row_mask:0xf bank_mask:0xf bound_ctrl:1
	v_pk_fma_f32 v[8:9], v[24:25], v[4:5], v[8:9]
	v_fmac_f32_e32 v36, v28, v33
	v_add_f32_dpp v34, v34, v34 row_ror:8 row_mask:0xf bank_mask:0xf bound_ctrl:1
	v_pk_fma_f32 v[22:23], v[14:15], v[34:35], v[6:7] op_sel_hi:[1,0,1]
	v_pk_fma_f32 v[24:25], v[16:17], v[34:35], v[8:9] op_sel_hi:[1,0,1]
	s_waitcnt lgkmcnt(3)
; template <int CTRL> __device__ __forceinline__ float dpp_f(float x) { return __int_as_float(__builtin_amdgcn_update_dpp(0, __float_as_int(x), CTRL, 0xf, 0xf, false)); }
; __device__ __forceinline__ void p8_scan(const Args& a, LAS unsigned char* lds) {
;     ...
;                 for (int tt = 0; tt < TC; ++tt) {
;                     ScanOps n; scan_ld(n, bt + (tt + 1 < TC ? tt + 1 : tt) * SPITCH, jq4, myrow);
;                     __builtin_amdgcn_sched_barrier(0);
;                     f32x2 ta = S01 * o.al.lo, ty = S01 * o.wr.lo; ta = S23 * o.al.hi + ta; ty = S23 * o.wr.hi + ty;
;                     float pa = ta.x + ta.y, py = ty.x + ty.y;
;                     f32x2 kv01 = o.kv.lo * o.vi, kv23 = o.kv.hi * o.vi;
;     ...
;                     asm volatile("" : "+v"(kv01), "+v"(kv23), "+v"(vc));
;                     pa += dpp_f<0x121>(pa); py += dpp_f<0x121>(py); pa += dpp_f<0x122>(pa); py += dpp_f<0x122>(py);
;                     pa += dpp_f<0x124>(pa); pa += dpp_f<0x128>(pa);
;                     S01 = S01 * o.wv.lo + (o.be.lo * pa + kv01);
;                     S23 = S23 * o.wv.hi + (o.be.hi * pa + kv23);
;     ...
;                     __builtin_amdgcn_sched_barrier(0);
;                     o = n;
	ds_read_b128 v[10:13], v38 offset:13056
	ds_read_b128 v[18:21], v38 offset:13568
	ds_read_b128 v[6:9], v38 offset:12800
	ds_read_b32 v28, v39 offset:13824
	ds_read_b128 v[2:5], v38 offset:12544
	ds_read_b32 v33, v40 offset:14084
	ds_read_b128 v[14:17], v38 offset:13312
	v_pk_mul_f32 v[34:35], v[22:23], v[50:51]
	v_pk_mul_f32 v[66:67], v[22:23], v[58:59]
	v_pk_fma_f32 v[34:35], v[24:25], v[52:53], v[34:35]
	v_pk_fma_f32 v[66:67], v[24:25], v[60:61], v[66:67]
	v_add_f32_e32 v34, v34, v35
	v_add_f32_e32 v66, v66, v67
	v_pk_mul_f32 v[46:47], v[46:47], v[62:63] op_sel_hi:[1,0]
	v_add_f32_dpp v34, v34, v34 row_ror:1 row_mask:0xf bank_mask:0xf bound_ctrl:1
	v_pk_mul_f32 v[48:49], v[48:49], v[62:63] op_sel_hi:[1,0]
	v_add_f32_dpp v66, v66, v66 row_ror:1 row_mask:0xf bank_mask:0xf bound_ctrl:1
	v_add_f32_dpp v34, v34, v34 row_ror:2 row_mask:0xf bank_mask:0xf bound_ctrl:1
	s_waitcnt lgkmcnt(7)
	v_pk_fma_f32 v[46:47], v[22:23], v[42:43], v[46:47]
	v_add_f32_dpp v66, v66, v66 row_ror:2 row_mask:0xf bank_mask:0xf bound_ctrl:1
	v_add_f32_dpp v34, v34, v34 row_ror:4 row_mask:0xf bank_mask:0xf bound_ctrl:1
	v_pk_fma_f32 v[48:49], v[24:25], v[44:45], v[48:49]
	v_fmac_f32_e32 v66, v62, v65
	v_add_f32_dpp v34, v34, v34 row_ror:8 row_mask:0xf bank_mask:0xf bound_ctrl:1
	v_pk_fma_f32 v[22:23], v[54:55], v[34:35], v[46:47] op_sel_hi:[1,0,1]
	v_pk_fma_f32 v[24:25], v[56:57], v[34:35], v[48:49] op_sel_hi:[1,0,1]
	ds_write2st64_b32 v41, v36, v66 offset0:6 offset1:7
	s_waitcnt lgkmcnt(4)
	ds_read_b128 v[50:53], v38 offset:14624
	ds_read_b128 v[58:61], v38 offset:15136
	ds_read_b128 v[46:49], v38 offset:14368
	ds_read_b32 v62, v39 offset:15392
	ds_read_b128 v[42:45], v38 offset:14112
	ds_read_b32 v65, v40 offset:15652
	ds_read_b128 v[54:57], v38 offset:14880
	v_pk_mul_f32 v[34:35], v[22:23], v[10:11]
	v_pk_mul_f32 v[36:37], v[22:23], v[18:19]
	v_pk_fma_f32 v[34:35], v[24:25], v[12:13], v[34:35]
	v_pk_fma_f32 v[36:37], v[24:25], v[20:21], v[36:37]
	v_add_f32_e32 v34, v34, v35
	v_add_f32_e32 v36, v36, v37
	v_pk_mul_f32 v[6:7], v[6:7], v[28:29] op_sel_hi:[1,0]
	v_add_f32_dpp v34, v34, v34 row_ror:1 row_mask:0xf bank_mask:0xf bound_ctrl:1
	v_pk_mul_f32 v[8:9], v[8:9], v[28:29] op_sel_hi:[1,0]
	v_add_f32_dpp v36, v36, v36 row_ror:1 row_mask:0xf bank_mask:0xf bound_ctrl:1
	v_add_f32_dpp v34, v34, v34 row_ror:2 row_mask:0xf bank_mask:0xf bound_ctrl:1
	s_waitcnt lgkmcnt(8)
	v_pk_fma_f32 v[6:7], v[22:23], v[2:3], v[6:7]
	v_add_f32_dpp v36, v36, v36 row_ror:2 row_mask:0xf bank_mask:0xf bound_ctrl:1
	v_add_f32_dpp v34, v34, v34 row_ror:4 row_mask:0xf bank_mask:0xf bound_ctrl:1
	v_pk_fma_f32 v[8:9], v[24:25], v[4:5], v[8:9]
	v_fmac_f32_e32 v36, v28, v33
	v_add_f32_dpp v34, v34, v34 row_ror:8 row_mask:0xf bank_mask:0xf bound_ctrl:1
	v_pk_fma_f32 v[22:23], v[14:15], v[34:35], v[6:7] op_sel_hi:[1,0,1]
	v_pk_fma_f32 v[24:25], v[16:17], v[34:35], v[8:9] op_sel_hi:[1,0,1]
	s_waitcnt lgkmcnt(3)
	ds_read_b128 v[10:13], v38 offset:16192
	ds_read_b128 v[18:21], v38 offset:16704
	ds_read_b128 v[6:9], v38 offset:15936
	ds_read_b32 v28, v39 offset:16960
	ds_read_b128 v[2:5], v38 offset:15680
	ds_read_b32 v33, v40 offset:17220
	ds_read_b128 v[14:17], v38 offset:16448
	v_pk_mul_f32 v[34:35], v[22:23], v[50:51]
	v_pk_mul_f32 v[66:67], v[22:23], v[58:59]
	v_pk_fma_f32 v[34:35], v[24:25], v[52:53], v[34:35]
	v_pk_fma_f32 v[66:67], v[24:25], v[60:61], v[66:67]
	v_add_f32_e32 v34, v34, v35
	v_add_f32_e32 v66, v66, v67
	v_pk_mul_f32 v[46:47], v[46:47], v[62:63] op_sel_hi:[1,0]
	v_add_f32_dpp v34, v34, v34 row_ror:1 row_mask:0xf bank_mask:0xf bound_ctrl:1
	v_pk_mul_f32 v[48:49], v[48:49], v[62:63] op_sel_hi:[1,0]
	v_add_f32_dpp v66, v66, v66 row_ror:1 row_mask:0xf bank_mask:0xf bound_ctrl:1
	v_add_f32_dpp v34, v34, v34 row_ror:2 row_mask:0xf bank_mask:0xf bound_ctrl:1
	s_waitcnt lgkmcnt(7)
	v_pk_fma_f32 v[46:47], v[22:23], v[42:43], v[46:47]
	v_add_f32_dpp v66, v66, v66 row_ror:2 row_mask:0xf bank_mask:0xf bound_ctrl:1
	v_add_f32_dpp v34, v34, v34 row_ror:4 row_mask:0xf bank_mask:0xf bound_ctrl:1
	v_pk_fma_f32 v[48:49], v[24:25], v[44:45], v[48:49]
	v_fmac_f32_e32 v66, v62, v65
	v_add_f32_dpp v34, v34, v34 row_ror:8 row_mask:0xf bank_mask:0xf bound_ctrl:1
	v_pk_fma_f32 v[22:23], v[54:55], v[34:35], v[46:47] op_sel_hi:[1,0,1]
	v_pk_fma_f32 v[24:25], v[56:57], v[34:35], v[48:49] op_sel_hi:[1,0,1]
	ds_write2st64_b32 v41, v36, v66 offset0:8 offset1:9
	s_waitcnt lgkmcnt(4)
	ds_read_b128 v[50:53], v38 offset:17760
	ds_read_b128 v[58:61], v38 offset:18272
	ds_read_b128 v[46:49], v38 offset:17504
	ds_read_b32 v62, v39 offset:18528
	ds_read_b128 v[42:45], v38 offset:17248
	ds_read_b32 v65, v40 offset:18788
	ds_read_b128 v[54:57], v38 offset:18016
	v_pk_mul_f32 v[34:35], v[22:23], v[10:11]
	v_pk_mul_f32 v[36:37], v[22:23], v[18:19]
	v_pk_fma_f32 v[34:35], v[24:25], v[12:13], v[34:35]
	v_pk_fma_f32 v[36:37], v[24:25], v[20:21], v[36:37]
	v_add_f32_e32 v34, v34, v35
	v_add_f32_e32 v36, v36, v37
	v_pk_mul_f32 v[6:7], v[6:7], v[28:29] op_sel_hi:[1,0]
	v_add_f32_dpp v34, v34, v34 row_ror:1 row_mask:0xf bank_mask:0xf bound_ctrl:1
	v_pk_mul_f32 v[8:9], v[8:9], v[28:29] op_sel_hi:[1,0]
	v_add_f32_dpp v36, v36, v36 row_ror:1 row_mask:0xf bank_mask:0xf bound_ctrl:1
	v_add_f32_dpp v34, v34, v34 row_ror:2 row_mask:0xf bank_mask:0xf bound_ctrl:1
	s_waitcnt lgkmcnt(8)
	v_pk_fma_f32 v[6:7], v[22:23], v[2:3], v[6:7]
	v_add_f32_dpp v36, v36, v36 row_ror:2 row_mask:0xf bank_mask:0xf bound_ctrl:1
	v_add_f32_dpp v34, v34, v34 row_ror:4 row_mask:0xf bank_mask:0xf bound_ctrl:1
	v_pk_fma_f32 v[8:9], v[24:25], v[4:5], v[8:9]
	v_fmac_f32_e32 v36, v28, v33
	v_add_f32_dpp v34, v34, v34 row_ror:8 row_mask:0xf bank_mask:0xf bound_ctrl:1
	v_pk_fma_f32 v[22:23], v[14:15], v[34:35], v[6:7] op_sel_hi:[1,0,1]
	v_pk_fma_f32 v[24:25], v[16:17], v[34:35], v[8:9] op_sel_hi:[1,0,1]
	s_waitcnt lgkmcnt(3)
; template <int CTRL> __device__ __forceinline__ float dpp_f(float x) { return __int_as_float(__builtin_amdgcn_update_dpp(0, __float_as_int(x), CTRL, 0xf, 0xf, false)); }
; __device__ __forceinline__ void p8_scan(const Args& a, LAS unsigned char* lds) {
;     ...
;                 for (int tt = 0; tt < TC; ++tt) {
;                     ScanOps n; scan_ld(n, bt + (tt + 1 < TC ? tt + 1 : tt) * SPITCH, jq4, myrow);
;                     __builtin_amdgcn_sched_barrier(0);
;                     f32x2 ta = S01 * o.al.lo, ty = S01 * o.wr.lo; ta = S23 * o.al.hi + ta; ty = S23 * o.wr.hi + ty;
;                     float pa = ta.x + ta.y, py = ty.x + ty.y;
;                     f32x2 kv01 = o.kv.lo * o.vi, kv23 = o.kv.hi * o.vi;
;     ...
;                     asm volatile("" : "+v"(kv01), "+v"(kv23), "+v"(vc));
;                     pa += dpp_f<0x121>(pa); py += dpp_f<0x121>(py); pa += dpp_f<0x122>(pa); py += dpp_f<0x122>(py);
;                     pa += dpp_f<0x124>(pa); pa += dpp_f<0x128>(pa);
;                     S01 = S01 * o.wv.lo + (o.be.lo * pa + kv01);
;                     S23 = S23 * o.wv.hi + (o.be.hi * pa + kv23);
;     ...
;                     __builtin_amdgcn_sched_barrier(0);
;                     o = n;
	ds_read_b128 v[10:13], v38 offset:19328
	ds_read_b128 v[18:21], v38 offset:19840
	ds_read_b128 v[6:9], v38 offset:19072
	ds_read_b32 v28, v39 offset:20096
	ds_read_b128 v[2:5], v38 offset:18816
	ds_read_b32 v33, v40 offset:20356
	ds_read_b128 v[14:17], v38 offset:19584
	v_pk_mul_f32 v[34:35], v[22:23], v[50:51]
	v_pk_mul_f32 v[66:67], v[22:23], v[58:59]
	v_pk_fma_f32 v[34:35], v[24:25], v[52:53], v[34:35]
	v_pk_fma_f32 v[66:67], v[24:25], v[60:61], v[66:67]
	v_add_f32_e32 v34, v34, v35
	v_add_f32_e32 v66, v66, v67
	v_pk_mul_f32 v[46:47], v[46:47], v[62:63] op_sel_hi:[1,0]
	v_add_f32_dpp v34, v34, v34 row_ror:1 row_mask:0xf bank_mask:0xf bound_ctrl:1
	v_pk_mul_f32 v[48:49], v[48:49], v[62:63] op_sel_hi:[1,0]
	v_add_f32_dpp v66, v66, v66 row_ror:1 row_mask:0xf bank_mask:0xf bound_ctrl:1
	v_add_f32_dpp v34, v34, v34 row_ror:2 row_mask:0xf bank_mask:0xf bound_ctrl:1
	s_waitcnt lgkmcnt(7)
	v_pk_fma_f32 v[46:47], v[22:23], v[42:43], v[46:47]
	v_add_f32_dpp v66, v66, v66 row_ror:2 row_mask:0xf bank_mask:0xf bound_ctrl:1
	v_add_f32_dpp v34, v34, v34 row_ror:4 row_mask:0xf bank_mask:0xf bound_ctrl:1
	v_pk_fma_f32 v[48:49], v[24:25], v[44:45], v[48:49]
	v_fmac_f32_e32 v66, v62, v65
	v_add_f32_dpp v34, v34, v34 row_ror:8 row_mask:0xf bank_mask:0xf bound_ctrl:1
	v_pk_fma_f32 v[22:23], v[54:55], v[34:35], v[46:47] op_sel_hi:[1,0,1]
	v_pk_fma_f32 v[24:25], v[56:57], v[34:35], v[48:49] op_sel_hi:[1,0,1]
	ds_write2st64_b32 v41, v36, v66 offset0:10 offset1:11
	s_waitcnt lgkmcnt(4)
	ds_read_b128 v[50:53], v38 offset:20896
	ds_read_b128 v[58:61], v38 offset:21408
	ds_read_b128 v[46:49], v38 offset:20640
	ds_read_b32 v62, v39 offset:21664
	ds_read_b128 v[42:45], v38 offset:20384
	ds_read_b32 v65, v40 offset:21924
	ds_read_b128 v[54:57], v38 offset:21152
	v_pk_mul_f32 v[34:35], v[22:23], v[10:11]
	v_pk_mul_f32 v[36:37], v[22:23], v[18:19]
	v_pk_fma_f32 v[34:35], v[24:25], v[12:13], v[34:35]
	v_pk_fma_f32 v[36:37], v[24:25], v[20:21], v[36:37]
	v_add_f32_e32 v34, v34, v35
	v_add_f32_e32 v36, v36, v37
	v_pk_mul_f32 v[6:7], v[6:7], v[28:29] op_sel_hi:[1,0]
	v_add_f32_dpp v34, v34, v34 row_ror:1 row_mask:0xf bank_mask:0xf bound_ctrl:1
	v_pk_mul_f32 v[8:9], v[8:9], v[28:29] op_sel_hi:[1,0]
	v_add_f32_dpp v36, v36, v36 row_ror:1 row_mask:0xf bank_mask:0xf bound_ctrl:1
	v_add_f32_dpp v34, v34, v34 row_ror:2 row_mask:0xf bank_mask:0xf bound_ctrl:1
	s_waitcnt lgkmcnt(8)
	v_pk_fma_f32 v[6:7], v[22:23], v[2:3], v[6:7]
	v_add_f32_dpp v36, v36, v36 row_ror:2 row_mask:0xf bank_mask:0xf bound_ctrl:1
	v_add_f32_dpp v34, v34, v34 row_ror:4 row_mask:0xf bank_mask:0xf bound_ctrl:1
	v_pk_fma_f32 v[8:9], v[24:25], v[4:5], v[8:9]
	v_fmac_f32_e32 v36, v28, v33
	v_add_f32_dpp v34, v34, v34 row_ror:8 row_mask:0xf bank_mask:0xf bound_ctrl:1
	v_pk_fma_f32 v[22:23], v[14:15], v[34:35], v[6:7] op_sel_hi:[1,0,1]
	v_pk_fma_f32 v[24:25], v[16:17], v[34:35], v[8:9] op_sel_hi:[1,0,1]
	s_waitcnt lgkmcnt(3)
	ds_read_b128 v[10:13], v38 offset:22464
	ds_read_b128 v[18:21], v38 offset:22976
	ds_read_b128 v[6:9], v38 offset:22208
	ds_read_b32 v28, v39 offset:23232
	ds_read_b128 v[2:5], v38 offset:21952
	ds_read_b32 v33, v40 offset:23492
	ds_read_b128 v[14:17], v38 offset:22720
	v_pk_mul_f32 v[34:35], v[22:23], v[50:51]
	v_pk_mul_f32 v[66:67], v[22:23], v[58:59]
	v_pk_fma_f32 v[34:35], v[24:25], v[52:53], v[34:35]
	v_pk_fma_f32 v[66:67], v[24:25], v[60:61], v[66:67]
	v_add_f32_e32 v34, v34, v35
	v_add_f32_e32 v66, v66, v67
	v_pk_mul_f32 v[46:47], v[46:47], v[62:63] op_sel_hi:[1,0]
	v_add_f32_dpp v34, v34, v34 row_ror:1 row_mask:0xf bank_mask:0xf bound_ctrl:1
	v_pk_mul_f32 v[48:49], v[48:49], v[62:63] op_sel_hi:[1,0]
	v_add_f32_dpp v66, v66, v66 row_ror:1 row_mask:0xf bank_mask:0xf bound_ctrl:1
	v_add_f32_dpp v34, v34, v34 row_ror:2 row_mask:0xf bank_mask:0xf bound_ctrl:1
	s_waitcnt lgkmcnt(7)
	v_pk_fma_f32 v[46:47], v[22:23], v[42:43], v[46:47]
	v_add_f32_dpp v66, v66, v66 row_ror:2 row_mask:0xf bank_mask:0xf bound_ctrl:1
	v_add_f32_dpp v34, v34, v34 row_ror:4 row_mask:0xf bank_mask:0xf bound_ctrl:1
	v_pk_fma_f32 v[48:49], v[24:25], v[44:45], v[48:49]
	v_fmac_f32_e32 v66, v62, v65
	v_add_f32_dpp v34, v34, v34 row_ror:8 row_mask:0xf bank_mask:0xf bound_ctrl:1
	v_pk_fma_f32 v[22:23], v[54:55], v[34:35], v[46:47] op_sel_hi:[1,0,1]
	v_pk_fma_f32 v[24:25], v[56:57], v[34:35], v[48:49] op_sel_hi:[1,0,1]
	ds_write2st64_b32 v41, v36, v66 offset0:12 offset1:13
	s_waitcnt lgkmcnt(4)
	ds_read_b128 v[50:53], v38 offset:24032
	ds_read_b128 v[58:61], v38 offset:24544
	ds_read_b128 v[46:49], v38 offset:23776
	ds_read_b32 v62, v39 offset:24800
	ds_read_b128 v[42:45], v38 offset:23520
	ds_read_b32 v65, v40 offset:25060
	ds_read_b128 v[54:57], v38 offset:24288
	v_pk_mul_f32 v[34:35], v[22:23], v[10:11]
	v_pk_mul_f32 v[36:37], v[22:23], v[18:19]
	v_pk_fma_f32 v[34:35], v[24:25], v[12:13], v[34:35]
	v_pk_fma_f32 v[36:37], v[24:25], v[20:21], v[36:37]
	v_add_f32_e32 v34, v34, v35
	v_add_f32_e32 v36, v36, v37
	v_pk_mul_f32 v[6:7], v[6:7], v[28:29] op_sel_hi:[1,0]
	v_add_f32_dpp v34, v34, v34 row_ror:1 row_mask:0xf bank_mask:0xf bound_ctrl:1
	v_pk_mul_f32 v[8:9], v[8:9], v[28:29] op_sel_hi:[1,0]
	v_add_f32_dpp v36, v36, v36 row_ror:1 row_mask:0xf bank_mask:0xf bound_ctrl:1
	v_add_f32_dpp v34, v34, v34 row_ror:2 row_mask:0xf bank_mask:0xf bound_ctrl:1
	s_waitcnt lgkmcnt(8)
	v_pk_fma_f32 v[6:7], v[22:23], v[2:3], v[6:7]
	v_add_f32_dpp v36, v36, v36 row_ror:2 row_mask:0xf bank_mask:0xf bound_ctrl:1
	v_add_f32_dpp v34, v34, v34 row_ror:4 row_mask:0xf bank_mask:0xf bound_ctrl:1
	v_pk_fma_f32 v[8:9], v[24:25], v[4:5], v[8:9]
	v_fmac_f32_e32 v36, v28, v33
	v_add_f32_dpp v34, v34, v34 row_ror:8 row_mask:0xf bank_mask:0xf bound_ctrl:1
	v_pk_fma_f32 v[22:23], v[14:15], v[34:35], v[6:7] op_sel_hi:[1,0,1]
	v_pk_fma_f32 v[24:25], v[16:17], v[34:35], v[8:9] op_sel_hi:[1,0,1]
	s_waitcnt lgkmcnt(3)
; template <int CTRL> __device__ __forceinline__ float dpp_f(float x) { return __int_as_float(__builtin_amdgcn_update_dpp(0, __float_as_int(x), CTRL, 0xf, 0xf, false)); }
; __device__ __forceinline__ void p8_scan(const Args& a, LAS unsigned char* lds) {
;     ...
;                 for (int tt = 0; tt < TC; ++tt) {
;                     ScanOps n; scan_ld(n, bt + (tt + 1 < TC ? tt + 1 : tt) * SPITCH, jq4, myrow);
;                     __builtin_amdgcn_sched_barrier(0);
;                     f32x2 ta = S01 * o.al.lo, ty = S01 * o.wr.lo; ta = S23 * o.al.hi + ta; ty = S23 * o.wr.hi + ty;
;                     float pa = ta.x + ta.y, py = ty.x + ty.y;
;                     f32x2 kv01 = o.kv.lo * o.vi, kv23 = o.kv.hi * o.vi;
;     ...
;                     asm volatile("" : "+v"(kv01), "+v"(kv23), "+v"(vc));
;                     pa += dpp_f<0x121>(pa); py += dpp_f<0x121>(py); pa += dpp_f<0x122>(pa); py += dpp_f<0x122>(py);
;                     pa += dpp_f<0x124>(pa); pa += dpp_f<0x128>(pa);
;                     S01 = S01 * o.wv.lo + (o.be.lo * pa + kv01);
;                     S23 = S23 * o.wv.hi + (o.be.hi * pa + kv23);
;     ...
;                     __builtin_amdgcn_sched_barrier(0);
;                     o = n;
	ds_read_b128 v[10:13], v38 offset:25600
	ds_read_b128 v[18:21], v38 offset:26112
	ds_read_b128 v[6:9], v38 offset:25344
	ds_read_b32 v28, v39 offset:26368
	ds_read_b128 v[2:5], v38 offset:25088
	ds_read_b32 v33, v40 offset:26628
	ds_read_b128 v[14:17], v38 offset:25856
	v_pk_mul_f32 v[34:35], v[22:23], v[50:51]
	v_pk_mul_f32 v[66:67], v[22:23], v[58:59]
	v_pk_fma_f32 v[34:35], v[24:25], v[52:53], v[34:35]
	v_pk_fma_f32 v[66:67], v[24:25], v[60:61], v[66:67]
	v_add_f32_e32 v34, v34, v35
	v_add_f32_e32 v66, v66, v67
	v_pk_mul_f32 v[46:47], v[46:47], v[62:63] op_sel_hi:[1,0]
	v_add_f32_dpp v34, v34, v34 row_ror:1 row_mask:0xf bank_mask:0xf bound_ctrl:1
	v_pk_mul_f32 v[48:49], v[48:49], v[62:63] op_sel_hi:[1,0]
	v_add_f32_dpp v66, v66, v66 row_ror:1 row_mask:0xf bank_mask:0xf bound_ctrl:1
	v_add_f32_dpp v34, v34, v34 row_ror:2 row_mask:0xf bank_mask:0xf bound_ctrl:1
	s_waitcnt lgkmcnt(7)
	v_pk_fma_f32 v[46:47], v[22:23], v[42:43], v[46:47]
	v_add_f32_dpp v66, v66, v66 row_ror:2 row_mask:0xf bank_mask:0xf bound_ctrl:1
	v_add_f32_dpp v34, v34, v34 row_ror:4 row_mask:0xf bank_mask:0xf bound_ctrl:1
	v_pk_fma_f32 v[48:49], v[24:25], v[44:45], v[48:49]
	v_fmac_f32_e32 v66, v62, v65
	v_add_f32_dpp v34, v34, v34 row_ror:8 row_mask:0xf bank_mask:0xf bound_ctrl:1
	v_pk_fma_f32 v[22:23], v[54:55], v[34:35], v[46:47] op_sel_hi:[1,0,1]
	v_pk_fma_f32 v[24:25], v[56:57], v[34:35], v[48:49] op_sel_hi:[1,0,1]
	ds_write2st64_b32 v41, v36, v66 offset0:14 offset1:15
	s_waitcnt lgkmcnt(4)
	ds_read_b128 v[50:53], v38 offset:27168
	ds_read_b128 v[58:61], v38 offset:27680
	ds_read_b128 v[46:49], v38 offset:26912
	ds_read_b32 v62, v39 offset:27936
	ds_read_b128 v[42:45], v38 offset:26656
	ds_read_b32 v65, v40 offset:28196
	ds_read_b128 v[54:57], v38 offset:27424
	v_pk_mul_f32 v[34:35], v[22:23], v[10:11]
	v_pk_mul_f32 v[36:37], v[22:23], v[18:19]
	v_pk_fma_f32 v[34:35], v[24:25], v[12:13], v[34:35]
	v_pk_fma_f32 v[36:37], v[24:25], v[20:21], v[36:37]
	v_add_f32_e32 v34, v34, v35
	v_add_f32_e32 v36, v36, v37
	v_pk_mul_f32 v[6:7], v[6:7], v[28:29] op_sel_hi:[1,0]
	v_add_f32_dpp v34, v34, v34 row_ror:1 row_mask:0xf bank_mask:0xf bound_ctrl:1
	v_pk_mul_f32 v[8:9], v[8:9], v[28:29] op_sel_hi:[1,0]
	v_add_f32_dpp v36, v36, v36 row_ror:1 row_mask:0xf bank_mask:0xf bound_ctrl:1
	v_add_f32_dpp v34, v34, v34 row_ror:2 row_mask:0xf bank_mask:0xf bound_ctrl:1
	s_waitcnt lgkmcnt(8)
	v_pk_fma_f32 v[6:7], v[22:23], v[2:3], v[6:7]
	v_add_f32_dpp v36, v36, v36 row_ror:2 row_mask:0xf bank_mask:0xf bound_ctrl:1
	v_add_f32_dpp v34, v34, v34 row_ror:4 row_mask:0xf bank_mask:0xf bound_ctrl:1
	v_pk_fma_f32 v[8:9], v[24:25], v[4:5], v[8:9]
	v_fmac_f32_e32 v36, v28, v33
	v_add_f32_dpp v34, v34, v34 row_ror:8 row_mask:0xf bank_mask:0xf bound_ctrl:1
	v_pk_fma_f32 v[22:23], v[14:15], v[34:35], v[6:7] op_sel_hi:[1,0,1]
	v_pk_fma_f32 v[24:25], v[16:17], v[34:35], v[8:9] op_sel_hi:[1,0,1]
	s_waitcnt lgkmcnt(3)
	ds_read_b128 v[10:13], v38 offset:28736
	ds_read_b128 v[18:21], v38 offset:29248
	ds_read_b128 v[6:9], v38 offset:28480
	ds_read_b32 v28, v39 offset:29504
	ds_read_b128 v[2:5], v38 offset:28224
	ds_read_b32 v33, v40 offset:29764
	ds_read_b128 v[14:17], v38 offset:28992
	v_pk_mul_f32 v[34:35], v[22:23], v[50:51]
	v_pk_mul_f32 v[66:67], v[22:23], v[58:59]
	v_pk_fma_f32 v[34:35], v[24:25], v[52:53], v[34:35]
	v_pk_fma_f32 v[66:67], v[24:25], v[60:61], v[66:67]
	v_add_f32_e32 v34, v34, v35
	v_add_f32_e32 v66, v66, v67
	v_pk_mul_f32 v[46:47], v[46:47], v[62:63] op_sel_hi:[1,0]
	v_add_f32_dpp v34, v34, v34 row_ror:1 row_mask:0xf bank_mask:0xf bound_ctrl:1
	v_pk_mul_f32 v[48:49], v[48:49], v[62:63] op_sel_hi:[1,0]
	v_add_f32_dpp v66, v66, v66 row_ror:1 row_mask:0xf bank_mask:0xf bound_ctrl:1
	v_add_f32_dpp v34, v34, v34 row_ror:2 row_mask:0xf bank_mask:0xf bound_ctrl:1
	s_waitcnt lgkmcnt(7)
	v_pk_fma_f32 v[46:47], v[22:23], v[42:43], v[46:47]
	v_add_f32_dpp v66, v66, v66 row_ror:2 row_mask:0xf bank_mask:0xf bound_ctrl:1
	v_add_f32_dpp v34, v34, v34 row_ror:4 row_mask:0xf bank_mask:0xf bound_ctrl:1
	v_pk_fma_f32 v[48:49], v[24:25], v[44:45], v[48:49]
	v_fmac_f32_e32 v66, v62, v65
	v_add_f32_dpp v34, v34, v34 row_ror:8 row_mask:0xf bank_mask:0xf bound_ctrl:1
	v_pk_fma_f32 v[22:23], v[54:55], v[34:35], v[46:47] op_sel_hi:[1,0,1]
	v_pk_fma_f32 v[24:25], v[56:57], v[34:35], v[48:49] op_sel_hi:[1,0,1]
	ds_write2st64_b32 v41, v36, v66 offset0:16 offset1:17
	s_waitcnt lgkmcnt(4)
	ds_read_b128 v[50:53], v38 offset:30304
	ds_read_b128 v[58:61], v38 offset:30816
	ds_read_b128 v[46:49], v38 offset:30048
	ds_read_b32 v62, v39 offset:31072
	ds_read_b128 v[42:45], v38 offset:29792
	ds_read_b32 v65, v40 offset:31332
	ds_read_b128 v[54:57], v38 offset:30560
	v_pk_mul_f32 v[34:35], v[22:23], v[10:11]
	v_pk_mul_f32 v[36:37], v[22:23], v[18:19]
	v_pk_fma_f32 v[34:35], v[24:25], v[12:13], v[34:35]
	v_pk_fma_f32 v[36:37], v[24:25], v[20:21], v[36:37]
	v_add_f32_e32 v34, v34, v35
	v_add_f32_e32 v36, v36, v37
	v_pk_mul_f32 v[6:7], v[6:7], v[28:29] op_sel_hi:[1,0]
	v_add_f32_dpp v34, v34, v34 row_ror:1 row_mask:0xf bank_mask:0xf bound_ctrl:1
	v_pk_mul_f32 v[8:9], v[8:9], v[28:29] op_sel_hi:[1,0]
	v_add_f32_dpp v36, v36, v36 row_ror:1 row_mask:0xf bank_mask:0xf bound_ctrl:1
	v_add_f32_dpp v34, v34, v34 row_ror:2 row_mask:0xf bank_mask:0xf bound_ctrl:1
	s_waitcnt lgkmcnt(8)
	v_pk_fma_f32 v[6:7], v[22:23], v[2:3], v[6:7]
	v_add_f32_dpp v36, v36, v36 row_ror:2 row_mask:0xf bank_mask:0xf bound_ctrl:1
	v_add_f32_dpp v34, v34, v34 row_ror:4 row_mask:0xf bank_mask:0xf bound_ctrl:1
	v_pk_fma_f32 v[8:9], v[24:25], v[4:5], v[8:9]
	v_fmac_f32_e32 v36, v28, v33
	v_add_f32_dpp v34, v34, v34 row_ror:8 row_mask:0xf bank_mask:0xf bound_ctrl:1
	v_pk_fma_f32 v[22:23], v[14:15], v[34:35], v[6:7] op_sel_hi:[1,0,1]
	v_pk_fma_f32 v[24:25], v[16:17], v[34:35], v[8:9] op_sel_hi:[1,0,1]
	s_waitcnt lgkmcnt(3)
; template <int CTRL> __device__ __forceinline__ float dpp_f(float x) { return __int_as_float(__builtin_amdgcn_update_dpp(0, __float_as_int(x), CTRL, 0xf, 0xf, false)); }
; __device__ __forceinline__ void p8_scan(const Args& a, LAS unsigned char* lds) {
;     ...
;                 for (int tt = 0; tt < TC; ++tt) {
;                     ScanOps n; scan_ld(n, bt + (tt + 1 < TC ? tt + 1 : tt) * SPITCH, jq4, myrow);
;                     __builtin_amdgcn_sched_barrier(0);
;                     f32x2 ta = S01 * o.al.lo, ty = S01 * o.wr.lo; ta = S23 * o.al.hi + ta; ty = S23 * o.wr.hi + ty;
;                     float pa = ta.x + ta.y, py = ty.x + ty.y;
;                     f32x2 kv01 = o.kv.lo * o.vi, kv23 = o.kv.hi * o.vi;
;     ...
;                     asm volatile("" : "+v"(kv01), "+v"(kv23), "+v"(vc));
;                     pa += dpp_f<0x121>(pa); py += dpp_f<0x121>(py); pa += dpp_f<0x122>(pa); py += dpp_f<0x122>(py);
;                     pa += dpp_f<0x124>(pa); pa += dpp_f<0x128>(pa);
;                     S01 = S01 * o.wv.lo + (o.be.lo * pa + kv01);
;                     S23 = S23 * o.wv.hi + (o.be.hi * pa + kv23);
;     ...
;                     __builtin_amdgcn_sched_barrier(0);
;                     o = n;
	ds_read_b128 v[10:13], v38 offset:31872
	ds_read_b128 v[18:21], v38 offset:32384
	ds_read_b128 v[6:9], v38 offset:31616
	ds_read_b32 v28, v39 offset:32640
	ds_read_b128 v[2:5], v38 offset:31360
	ds_read_b32 v33, v40 offset:32900
	ds_read_b128 v[14:17], v38 offset:32128
	v_pk_mul_f32 v[34:35], v[22:23], v[50:51]
	v_pk_mul_f32 v[66:67], v[22:23], v[58:59]
	v_pk_fma_f32 v[34:35], v[24:25], v[52:53], v[34:35]
	v_pk_fma_f32 v[66:67], v[24:25], v[60:61], v[66:67]
	v_add_f32_e32 v34, v34, v35
	v_add_f32_e32 v66, v66, v67
	v_pk_mul_f32 v[46:47], v[46:47], v[62:63] op_sel_hi:[1,0]
	v_add_f32_dpp v34, v34, v34 row_ror:1 row_mask:0xf bank_mask:0xf bound_ctrl:1
	v_pk_mul_f32 v[48:49], v[48:49], v[62:63] op_sel_hi:[1,0]
	v_add_f32_dpp v66, v66, v66 row_ror:1 row_mask:0xf bank_mask:0xf bound_ctrl:1
	v_add_f32_dpp v34, v34, v34 row_ror:2 row_mask:0xf bank_mask:0xf bound_ctrl:1
	s_waitcnt lgkmcnt(7)
	v_pk_fma_f32 v[46:47], v[22:23], v[42:43], v[46:47]
	v_add_f32_dpp v66, v66, v66 row_ror:2 row_mask:0xf bank_mask:0xf bound_ctrl:1
	v_add_f32_dpp v34, v34, v34 row_ror:4 row_mask:0xf bank_mask:0xf bound_ctrl:1
	v_pk_fma_f32 v[48:49], v[24:25], v[44:45], v[48:49]
	v_fmac_f32_e32 v66, v62, v65
	v_add_f32_dpp v34, v34, v34 row_ror:8 row_mask:0xf bank_mask:0xf bound_ctrl:1
	v_pk_fma_f32 v[22:23], v[54:55], v[34:35], v[46:47] op_sel_hi:[1,0,1]
	v_pk_fma_f32 v[24:25], v[56:57], v[34:35], v[48:49] op_sel_hi:[1,0,1]
	ds_write2st64_b32 v41, v36, v66 offset0:18 offset1:19
	s_waitcnt lgkmcnt(4)
	ds_read_b128 v[50:53], v38 offset:33440
	ds_read_b128 v[58:61], v38 offset:33952
	ds_read_b128 v[46:49], v38 offset:33184
	ds_read_b32 v62, v39 offset:34208
	ds_read_b128 v[42:45], v38 offset:32928
	ds_read_b32 v65, v40 offset:34468
	ds_read_b128 v[54:57], v38 offset:33696
	v_pk_mul_f32 v[34:35], v[22:23], v[10:11]
	v_pk_mul_f32 v[36:37], v[22:23], v[18:19]
	v_pk_fma_f32 v[34:35], v[24:25], v[12:13], v[34:35]
	v_pk_fma_f32 v[36:37], v[24:25], v[20:21], v[36:37]
	v_add_f32_e32 v34, v34, v35
	v_add_f32_e32 v36, v36, v37
	v_pk_mul_f32 v[6:7], v[6:7], v[28:29] op_sel_hi:[1,0]
	v_add_f32_dpp v34, v34, v34 row_ror:1 row_mask:0xf bank_mask:0xf bound_ctrl:1
	v_pk_mul_f32 v[8:9], v[8:9], v[28:29] op_sel_hi:[1,0]
	v_add_f32_dpp v36, v36, v36 row_ror:1 row_mask:0xf bank_mask:0xf bound_ctrl:1
	v_add_f32_dpp v34, v34, v34 row_ror:2 row_mask:0xf bank_mask:0xf bound_ctrl:1
	s_waitcnt lgkmcnt(8)
	v_pk_fma_f32 v[6:7], v[22:23], v[2:3], v[6:7]
	v_add_f32_dpp v36, v36, v36 row_ror:2 row_mask:0xf bank_mask:0xf bound_ctrl:1
	v_add_f32_dpp v34, v34, v34 row_ror:4 row_mask:0xf bank_mask:0xf bound_ctrl:1
	v_pk_fma_f32 v[8:9], v[24:25], v[4:5], v[8:9]
	v_fmac_f32_e32 v36, v28, v33
	v_add_f32_dpp v34, v34, v34 row_ror:8 row_mask:0xf bank_mask:0xf bound_ctrl:1
	v_pk_fma_f32 v[22:23], v[14:15], v[34:35], v[6:7] op_sel_hi:[1,0,1]
	v_pk_fma_f32 v[24:25], v[16:17], v[34:35], v[8:9] op_sel_hi:[1,0,1]
	s_waitcnt lgkmcnt(3)
	ds_read_b128 v[10:13], v38 offset:35008
	ds_read_b128 v[18:21], v38 offset:35520
	ds_read_b128 v[6:9], v38 offset:34752
	ds_read_b32 v28, v39 offset:35776
	ds_read_b128 v[2:5], v38 offset:34496
	ds_read_b32 v33, v40 offset:36036
	ds_read_b128 v[14:17], v38 offset:35264
	v_pk_mul_f32 v[34:35], v[22:23], v[50:51]
	v_pk_mul_f32 v[66:67], v[22:23], v[58:59]
	v_pk_fma_f32 v[34:35], v[24:25], v[52:53], v[34:35]
	v_pk_fma_f32 v[66:67], v[24:25], v[60:61], v[66:67]
	v_add_f32_e32 v34, v34, v35
	v_add_f32_e32 v66, v66, v67
	v_pk_mul_f32 v[46:47], v[46:47], v[62:63] op_sel_hi:[1,0]
	v_add_f32_dpp v34, v34, v34 row_ror:1 row_mask:0xf bank_mask:0xf bound_ctrl:1
	v_pk_mul_f32 v[48:49], v[48:49], v[62:63] op_sel_hi:[1,0]
	v_add_f32_dpp v66, v66, v66 row_ror:1 row_mask:0xf bank_mask:0xf bound_ctrl:1
	v_add_f32_dpp v34, v34, v34 row_ror:2 row_mask:0xf bank_mask:0xf bound_ctrl:1
	s_waitcnt lgkmcnt(7)
	v_pk_fma_f32 v[46:47], v[22:23], v[42:43], v[46:47]
	v_add_f32_dpp v66, v66, v66 row_ror:2 row_mask:0xf bank_mask:0xf bound_ctrl:1
	v_add_f32_dpp v34, v34, v34 row_ror:4 row_mask:0xf bank_mask:0xf bound_ctrl:1
	v_pk_fma_f32 v[48:49], v[24:25], v[44:45], v[48:49]
	v_fmac_f32_e32 v66, v62, v65
	v_add_f32_dpp v34, v34, v34 row_ror:8 row_mask:0xf bank_mask:0xf bound_ctrl:1
	v_pk_fma_f32 v[22:23], v[54:55], v[34:35], v[46:47] op_sel_hi:[1,0,1]
	v_pk_fma_f32 v[24:25], v[56:57], v[34:35], v[48:49] op_sel_hi:[1,0,1]
	ds_write2st64_b32 v41, v36, v66 offset0:20 offset1:21
	s_waitcnt lgkmcnt(4)
	ds_read_b128 v[50:53], v38 offset:36576
	ds_read_b128 v[58:61], v38 offset:37088
	ds_read_b128 v[46:49], v38 offset:36320
	ds_read_b32 v62, v39 offset:37344
	ds_read_b128 v[42:45], v38 offset:36064
	ds_read_b32 v65, v40 offset:37604
	ds_read_b128 v[54:57], v38 offset:36832
	v_pk_mul_f32 v[34:35], v[22:23], v[10:11]
	v_pk_mul_f32 v[36:37], v[22:23], v[18:19]
	v_pk_fma_f32 v[34:35], v[24:25], v[12:13], v[34:35]
	v_pk_fma_f32 v[36:37], v[24:25], v[20:21], v[36:37]
	v_add_f32_e32 v34, v34, v35
	v_add_f32_e32 v36, v36, v37
	v_pk_mul_f32 v[6:7], v[6:7], v[28:29] op_sel_hi:[1,0]
	v_add_f32_dpp v34, v34, v34 row_ror:1 row_mask:0xf bank_mask:0xf bound_ctrl:1
	v_pk_mul_f32 v[8:9], v[8:9], v[28:29] op_sel_hi:[1,0]
	v_add_f32_dpp v36, v36, v36 row_ror:1 row_mask:0xf bank_mask:0xf bound_ctrl:1
	v_add_f32_dpp v34, v34, v34 row_ror:2 row_mask:0xf bank_mask:0xf bound_ctrl:1
	s_waitcnt lgkmcnt(8)
	v_pk_fma_f32 v[6:7], v[22:23], v[2:3], v[6:7]
	v_add_f32_dpp v36, v36, v36 row_ror:2 row_mask:0xf bank_mask:0xf bound_ctrl:1
	v_add_f32_dpp v34, v34, v34 row_ror:4 row_mask:0xf bank_mask:0xf bound_ctrl:1
	v_pk_fma_f32 v[8:9], v[24:25], v[4:5], v[8:9]
	v_fmac_f32_e32 v36, v28, v33
	v_add_f32_dpp v34, v34, v34 row_ror:8 row_mask:0xf bank_mask:0xf bound_ctrl:1
	v_pk_fma_f32 v[22:23], v[14:15], v[34:35], v[6:7] op_sel_hi:[1,0,1]
	v_pk_fma_f32 v[24:25], v[16:17], v[34:35], v[8:9] op_sel_hi:[1,0,1]
	s_waitcnt lgkmcnt(3)
; template <int CTRL> __device__ __forceinline__ float dpp_f(float x) { return __int_as_float(__builtin_amdgcn_update_dpp(0, __float_as_int(x), CTRL, 0xf, 0xf, false)); }
; __device__ __forceinline__ void p8_scan(const Args& a, LAS unsigned char* lds) {
;     ...
;                 for (int tt = 0; tt < TC; ++tt) {
;                     ScanOps n; scan_ld(n, bt + (tt + 1 < TC ? tt + 1 : tt) * SPITCH, jq4, myrow);
;                     __builtin_amdgcn_sched_barrier(0);
;                     f32x2 ta = S01 * o.al.lo, ty = S01 * o.wr.lo; ta = S23 * o.al.hi + ta; ty = S23 * o.wr.hi + ty;
;                     float pa = ta.x + ta.y, py = ty.x + ty.y;
;                     f32x2 kv01 = o.kv.lo * o.vi, kv23 = o.kv.hi * o.vi;
;     ...
;                     asm volatile("" : "+v"(kv01), "+v"(kv23), "+v"(vc));
;                     pa += dpp_f<0x121>(pa); py += dpp_f<0x121>(py); pa += dpp_f<0x122>(pa); py += dpp_f<0x122>(py);
;                     pa += dpp_f<0x124>(pa); pa += dpp_f<0x128>(pa);
;                     S01 = S01 * o.wv.lo + (o.be.lo * pa + kv01);
;                     S23 = S23 * o.wv.hi + (o.be.hi * pa + kv23);
;     ...
;                     __builtin_amdgcn_sched_barrier(0);
;                     o = n;
	ds_read_b128 v[10:13], v38 offset:38144
	ds_read_b128 v[18:21], v38 offset:38656
	ds_read_b128 v[6:9], v38 offset:37888
	ds_read_b32 v28, v39 offset:38912
	ds_read_b128 v[2:5], v38 offset:37632
	ds_read_b32 v33, v40 offset:39172
	ds_read_b128 v[14:17], v38 offset:38400
	v_pk_mul_f32 v[34:35], v[22:23], v[50:51]
	v_pk_mul_f32 v[66:67], v[22:23], v[58:59]
	v_pk_fma_f32 v[34:35], v[24:25], v[52:53], v[34:35]
	v_pk_fma_f32 v[66:67], v[24:25], v[60:61], v[66:67]
	v_add_f32_e32 v34, v34, v35
	v_add_f32_e32 v66, v66, v67
	v_pk_mul_f32 v[46:47], v[46:47], v[62:63] op_sel_hi:[1,0]
	v_add_f32_dpp v34, v34, v34 row_ror:1 row_mask:0xf bank_mask:0xf bound_ctrl:1
	v_pk_mul_f32 v[48:49], v[48:49], v[62:63] op_sel_hi:[1,0]
	v_add_f32_dpp v66, v66, v66 row_ror:1 row_mask:0xf bank_mask:0xf bound_ctrl:1
	v_add_f32_dpp v34, v34, v34 row_ror:2 row_mask:0xf bank_mask:0xf bound_ctrl:1
	s_waitcnt lgkmcnt(7)
	v_pk_fma_f32 v[46:47], v[22:23], v[42:43], v[46:47]
	v_add_f32_dpp v66, v66, v66 row_ror:2 row_mask:0xf bank_mask:0xf bound_ctrl:1
	v_add_f32_dpp v34, v34, v34 row_ror:4 row_mask:0xf bank_mask:0xf bound_ctrl:1
	v_pk_fma_f32 v[48:49], v[24:25], v[44:45], v[48:49]
	v_fmac_f32_e32 v66, v62, v65
	v_add_f32_dpp v34, v34, v34 row_ror:8 row_mask:0xf bank_mask:0xf bound_ctrl:1
	v_pk_fma_f32 v[22:23], v[54:55], v[34:35], v[46:47] op_sel_hi:[1,0,1]
	v_pk_fma_f32 v[24:25], v[56:57], v[34:35], v[48:49] op_sel_hi:[1,0,1]
	ds_write2st64_b32 v41, v36, v66 offset0:22 offset1:23
	s_waitcnt lgkmcnt(4)
	ds_read_b128 v[50:53], v38 offset:39712
	ds_read_b128 v[58:61], v38 offset:40224
	ds_read_b128 v[46:49], v38 offset:39456
	ds_read_b32 v62, v39 offset:40480
	ds_read_b128 v[42:45], v38 offset:39200
	ds_read_b32 v65, v40 offset:40740
	ds_read_b128 v[54:57], v38 offset:39968
	v_pk_mul_f32 v[34:35], v[22:23], v[10:11]
	v_pk_mul_f32 v[36:37], v[22:23], v[18:19]
	v_pk_fma_f32 v[34:35], v[24:25], v[12:13], v[34:35]
	v_pk_fma_f32 v[36:37], v[24:25], v[20:21], v[36:37]
	v_add_f32_e32 v34, v34, v35
	v_add_f32_e32 v36, v36, v37
	v_pk_mul_f32 v[6:7], v[6:7], v[28:29] op_sel_hi:[1,0]
	v_add_f32_dpp v34, v34, v34 row_ror:1 row_mask:0xf bank_mask:0xf bound_ctrl:1
	v_pk_mul_f32 v[8:9], v[8:9], v[28:29] op_sel_hi:[1,0]
	v_add_f32_dpp v36, v36, v36 row_ror:1 row_mask:0xf bank_mask:0xf bound_ctrl:1
	v_add_f32_dpp v34, v34, v34 row_ror:2 row_mask:0xf bank_mask:0xf bound_ctrl:1
	s_waitcnt lgkmcnt(8)
	v_pk_fma_f32 v[6:7], v[22:23], v[2:3], v[6:7]
	v_add_f32_dpp v36, v36, v36 row_ror:2 row_mask:0xf bank_mask:0xf bound_ctrl:1
	v_add_f32_dpp v34, v34, v34 row_ror:4 row_mask:0xf bank_mask:0xf bound_ctrl:1
	v_pk_fma_f32 v[8:9], v[24:25], v[4:5], v[8:9]
	v_fmac_f32_e32 v36, v28, v33
	v_add_f32_dpp v34, v34, v34 row_ror:8 row_mask:0xf bank_mask:0xf bound_ctrl:1
	v_pk_fma_f32 v[22:23], v[14:15], v[34:35], v[6:7] op_sel_hi:[1,0,1]
	v_pk_fma_f32 v[24:25], v[16:17], v[34:35], v[8:9] op_sel_hi:[1,0,1]
	s_waitcnt lgkmcnt(3)
	ds_read_b128 v[10:13], v38 offset:41280
	ds_read_b128 v[18:21], v38 offset:41792
	ds_read_b128 v[6:9], v38 offset:41024
	ds_read_b32 v28, v39 offset:42048
	ds_read_b128 v[2:5], v38 offset:40768
	ds_read_b32 v33, v40 offset:42308
	ds_read_b128 v[14:17], v38 offset:41536
	v_pk_mul_f32 v[34:35], v[22:23], v[50:51]
	v_pk_mul_f32 v[66:67], v[22:23], v[58:59]
	v_pk_fma_f32 v[34:35], v[24:25], v[52:53], v[34:35]
	v_pk_fma_f32 v[66:67], v[24:25], v[60:61], v[66:67]
	v_add_f32_e32 v34, v34, v35
	v_add_f32_e32 v66, v66, v67
	v_pk_mul_f32 v[46:47], v[46:47], v[62:63] op_sel_hi:[1,0]
	v_add_f32_dpp v34, v34, v34 row_ror:1 row_mask:0xf bank_mask:0xf bound_ctrl:1
	v_pk_mul_f32 v[48:49], v[48:49], v[62:63] op_sel_hi:[1,0]
	v_add_f32_dpp v66, v66, v66 row_ror:1 row_mask:0xf bank_mask:0xf bound_ctrl:1
	v_add_f32_dpp v34, v34, v34 row_ror:2 row_mask:0xf bank_mask:0xf bound_ctrl:1
	s_waitcnt lgkmcnt(7)
	v_pk_fma_f32 v[46:47], v[22:23], v[42:43], v[46:47]
	v_add_f32_dpp v66, v66, v66 row_ror:2 row_mask:0xf bank_mask:0xf bound_ctrl:1
	v_add_f32_dpp v34, v34, v34 row_ror:4 row_mask:0xf bank_mask:0xf bound_ctrl:1
	v_pk_fma_f32 v[48:49], v[24:25], v[44:45], v[48:49]
	v_fmac_f32_e32 v66, v62, v65
	v_add_f32_dpp v34, v34, v34 row_ror:8 row_mask:0xf bank_mask:0xf bound_ctrl:1
	v_pk_fma_f32 v[22:23], v[54:55], v[34:35], v[46:47] op_sel_hi:[1,0,1]
	v_pk_fma_f32 v[24:25], v[56:57], v[34:35], v[48:49] op_sel_hi:[1,0,1]
	ds_write2st64_b32 v41, v36, v66 offset0:24 offset1:25
	s_waitcnt lgkmcnt(4)
	ds_read_b128 v[50:53], v38 offset:42848
	ds_read_b128 v[58:61], v38 offset:43360
	ds_read_b128 v[46:49], v38 offset:42592
	ds_read_b32 v62, v39 offset:43616
	ds_read_b128 v[42:45], v38 offset:42336
	ds_read_b32 v65, v40 offset:43876
	ds_read_b128 v[54:57], v38 offset:43104
	v_pk_mul_f32 v[34:35], v[22:23], v[10:11]
	v_pk_mul_f32 v[36:37], v[22:23], v[18:19]
	v_pk_fma_f32 v[34:35], v[24:25], v[12:13], v[34:35]
	v_pk_fma_f32 v[36:37], v[24:25], v[20:21], v[36:37]
	v_add_f32_e32 v34, v34, v35
	v_add_f32_e32 v36, v36, v37
	v_pk_mul_f32 v[6:7], v[6:7], v[28:29] op_sel_hi:[1,0]
	v_add_f32_dpp v34, v34, v34 row_ror:1 row_mask:0xf bank_mask:0xf bound_ctrl:1
	v_pk_mul_f32 v[8:9], v[8:9], v[28:29] op_sel_hi:[1,0]
	v_add_f32_dpp v36, v36, v36 row_ror:1 row_mask:0xf bank_mask:0xf bound_ctrl:1
	v_add_f32_dpp v34, v34, v34 row_ror:2 row_mask:0xf bank_mask:0xf bound_ctrl:1
	s_waitcnt lgkmcnt(8)
	v_pk_fma_f32 v[6:7], v[22:23], v[2:3], v[6:7]
	v_add_f32_dpp v36, v36, v36 row_ror:2 row_mask:0xf bank_mask:0xf bound_ctrl:1
	v_add_f32_dpp v34, v34, v34 row_ror:4 row_mask:0xf bank_mask:0xf bound_ctrl:1
	v_pk_fma_f32 v[8:9], v[24:25], v[4:5], v[8:9]
	v_fmac_f32_e32 v36, v28, v33
	v_add_f32_dpp v34, v34, v34 row_ror:8 row_mask:0xf bank_mask:0xf bound_ctrl:1
	v_pk_fma_f32 v[22:23], v[14:15], v[34:35], v[6:7] op_sel_hi:[1,0,1]
	v_pk_fma_f32 v[24:25], v[16:17], v[34:35], v[8:9] op_sel_hi:[1,0,1]
	s_waitcnt lgkmcnt(3)
; template <int CTRL> __device__ __forceinline__ float dpp_f(float x) { return __int_as_float(__builtin_amdgcn_update_dpp(0, __float_as_int(x), CTRL, 0xf, 0xf, false)); }
; __device__ __forceinline__ void p8_scan(const Args& a, LAS unsigned char* lds) {
;     ...
;                 for (int tt = 0; tt < TC; ++tt) {
;                     ScanOps n; scan_ld(n, bt + (tt + 1 < TC ? tt + 1 : tt) * SPITCH, jq4, myrow);
;                     __builtin_amdgcn_sched_barrier(0);
;                     f32x2 ta = S01 * o.al.lo, ty = S01 * o.wr.lo; ta = S23 * o.al.hi + ta; ty = S23 * o.wr.hi + ty;
;                     float pa = ta.x + ta.y, py = ty.x + ty.y;
;                     f32x2 kv01 = o.kv.lo * o.vi, kv23 = o.kv.hi * o.vi;
;     ...
;                     asm volatile("" : "+v"(kv01), "+v"(kv23), "+v"(vc));
;                     pa += dpp_f<0x121>(pa); py += dpp_f<0x121>(py); pa += dpp_f<0x122>(pa); py += dpp_f<0x122>(py);
;                     pa += dpp_f<0x124>(pa); pa += dpp_f<0x128>(pa);
;                     S01 = S01 * o.wv.lo + (o.be.lo * pa + kv01);
;                     S23 = S23 * o.wv.hi + (o.be.hi * pa + kv23);
;     ...
;                     __builtin_amdgcn_sched_barrier(0);
;                     o = n;
	ds_read_b128 v[10:13], v38 offset:44416
	ds_read_b128 v[18:21], v38 offset:44928
	ds_read_b128 v[6:9], v38 offset:44160
	ds_read_b32 v28, v39 offset:45184
	ds_read_b128 v[2:5], v38 offset:43904
	ds_read_b32 v33, v40 offset:45444
	ds_read_b128 v[14:17], v38 offset:44672
	v_pk_mul_f32 v[34:35], v[22:23], v[50:51]
	v_pk_mul_f32 v[66:67], v[22:23], v[58:59]
	v_pk_fma_f32 v[34:35], v[24:25], v[52:53], v[34:35]
	v_pk_fma_f32 v[66:67], v[24:25], v[60:61], v[66:67]
	v_add_f32_e32 v34, v34, v35
	v_add_f32_e32 v66, v66, v67
	v_pk_mul_f32 v[46:47], v[46:47], v[62:63] op_sel_hi:[1,0]
	v_add_f32_dpp v34, v34, v34 row_ror:1 row_mask:0xf bank_mask:0xf bound_ctrl:1
	v_pk_mul_f32 v[48:49], v[48:49], v[62:63] op_sel_hi:[1,0]
	v_add_f32_dpp v66, v66, v66 row_ror:1 row_mask:0xf bank_mask:0xf bound_ctrl:1
	v_add_f32_dpp v34, v34, v34 row_ror:2 row_mask:0xf bank_mask:0xf bound_ctrl:1
	s_waitcnt lgkmcnt(7)
	v_pk_fma_f32 v[46:47], v[22:23], v[42:43], v[46:47]
	v_add_f32_dpp v66, v66, v66 row_ror:2 row_mask:0xf bank_mask:0xf bound_ctrl:1
	v_add_f32_dpp v34, v34, v34 row_ror:4 row_mask:0xf bank_mask:0xf bound_ctrl:1
	v_pk_fma_f32 v[48:49], v[24:25], v[44:45], v[48:49]
	v_fmac_f32_e32 v66, v62, v65
	v_add_f32_dpp v34, v34, v34 row_ror:8 row_mask:0xf bank_mask:0xf bound_ctrl:1
	v_pk_fma_f32 v[22:23], v[54:55], v[34:35], v[46:47] op_sel_hi:[1,0,1]
	v_pk_fma_f32 v[24:25], v[56:57], v[34:35], v[48:49] op_sel_hi:[1,0,1]
	ds_write2st64_b32 v41, v36, v66 offset0:26 offset1:27
	s_waitcnt lgkmcnt(4)
	ds_read_b128 v[50:53], v38 offset:45984
	ds_read_b128 v[58:61], v38 offset:46496
	ds_read_b128 v[46:49], v38 offset:45728
	ds_read_b32 v62, v39 offset:46752
	ds_read_b128 v[42:45], v38 offset:45472
	ds_read_b32 v65, v40 offset:47012
	ds_read_b128 v[54:57], v38 offset:46240
	v_pk_mul_f32 v[34:35], v[22:23], v[10:11]
	v_pk_mul_f32 v[36:37], v[22:23], v[18:19]
	v_pk_fma_f32 v[34:35], v[24:25], v[12:13], v[34:35]
	v_pk_fma_f32 v[36:37], v[24:25], v[20:21], v[36:37]
	v_add_f32_e32 v34, v34, v35
	v_add_f32_e32 v36, v36, v37
	v_pk_mul_f32 v[6:7], v[6:7], v[28:29] op_sel_hi:[1,0]
	v_add_f32_dpp v34, v34, v34 row_ror:1 row_mask:0xf bank_mask:0xf bound_ctrl:1
	v_pk_mul_f32 v[8:9], v[8:9], v[28:29] op_sel_hi:[1,0]
	v_add_f32_dpp v36, v36, v36 row_ror:1 row_mask:0xf bank_mask:0xf bound_ctrl:1
	v_add_f32_dpp v34, v34, v34 row_ror:2 row_mask:0xf bank_mask:0xf bound_ctrl:1
	s_waitcnt lgkmcnt(8)
	v_pk_fma_f32 v[6:7], v[22:23], v[2:3], v[6:7]
	v_add_f32_dpp v36, v36, v36 row_ror:2 row_mask:0xf bank_mask:0xf bound_ctrl:1
	v_add_f32_dpp v34, v34, v34 row_ror:4 row_mask:0xf bank_mask:0xf bound_ctrl:1
	v_pk_fma_f32 v[8:9], v[24:25], v[4:5], v[8:9]
	v_fmac_f32_e32 v36, v28, v33
	v_add_f32_dpp v34, v34, v34 row_ror:8 row_mask:0xf bank_mask:0xf bound_ctrl:1
	v_pk_fma_f32 v[22:23], v[14:15], v[34:35], v[6:7] op_sel_hi:[1,0,1]
	v_pk_fma_f32 v[24:25], v[16:17], v[34:35], v[8:9] op_sel_hi:[1,0,1]
	s_waitcnt lgkmcnt(3)
	ds_read_b128 v[10:13], v38 offset:47552
	ds_read_b128 v[18:21], v38 offset:48064
	ds_read_b128 v[6:9], v38 offset:47296
	ds_read_b32 v28, v39 offset:48320
	ds_read_b128 v[2:5], v38 offset:47040
	ds_read_b32 v33, v40 offset:48580
	ds_read_b128 v[14:17], v38 offset:47808
	v_pk_mul_f32 v[34:35], v[22:23], v[50:51]
	v_pk_mul_f32 v[66:67], v[22:23], v[58:59]
	v_pk_fma_f32 v[34:35], v[24:25], v[52:53], v[34:35]
	v_pk_fma_f32 v[66:67], v[24:25], v[60:61], v[66:67]
	v_add_f32_e32 v34, v34, v35
	v_add_f32_e32 v66, v66, v67
	v_pk_mul_f32 v[46:47], v[46:47], v[62:63] op_sel_hi:[1,0]
	v_add_f32_dpp v34, v34, v34 row_ror:1 row_mask:0xf bank_mask:0xf bound_ctrl:1
	v_pk_mul_f32 v[48:49], v[48:49], v[62:63] op_sel_hi:[1,0]
	v_add_f32_dpp v66, v66, v66 row_ror:1 row_mask:0xf bank_mask:0xf bound_ctrl:1
	v_add_f32_dpp v34, v34, v34 row_ror:2 row_mask:0xf bank_mask:0xf bound_ctrl:1
	s_waitcnt lgkmcnt(7)
; template <int CTRL> __device__ __forceinline__ float dpp_f(float x) { return __int_as_float(__builtin_amdgcn_update_dpp(0, __float_as_int(x), CTRL, 0xf, 0xf, false)); }
; __device__ __forceinline__ void p8_scan(const Args& a, LAS unsigned char* lds) {
;     ...
;                 for (int tt = 0; tt < TC; ++tt) {
;                     ScanOps n; scan_ld(n, bt + (tt + 1 < TC ? tt + 1 : tt) * SPITCH, jq4, myrow);
;                     __builtin_amdgcn_sched_barrier(0);
;                     f32x2 ta = S01 * o.al.lo, ty = S01 * o.wr.lo; ta = S23 * o.al.hi + ta; ty = S23 * o.wr.hi + ty;
;                     float pa = ta.x + ta.y, py = ty.x + ty.y;
;                     f32x2 kv01 = o.kv.lo * o.vi, kv23 = o.kv.hi * o.vi;
;     ...
;                     asm volatile("" : "+v"(kv01), "+v"(kv23), "+v"(vc));
;                     pa += dpp_f<0x121>(pa); py += dpp_f<0x121>(py); pa += dpp_f<0x122>(pa); py += dpp_f<0x122>(py);
;                     pa += dpp_f<0x124>(pa); pa += dpp_f<0x128>(pa);
;                     S01 = S01 * o.wv.lo + (o.be.lo * pa + kv01);
;                     S23 = S23 * o.wv.hi + (o.be.hi * pa + kv23);
;     ...
;                     __builtin_amdgcn_sched_barrier(0);
;                     o = n;
;                 }
;                 __syncthreads();
;             }
	v_pk_fma_f32 v[46:47], v[22:23], v[42:43], v[46:47]
	v_add_f32_dpp v66, v66, v66 row_ror:2 row_mask:0xf bank_mask:0xf bound_ctrl:1
	v_add_f32_dpp v34, v34, v34 row_ror:4 row_mask:0xf bank_mask:0xf bound_ctrl:1
	v_pk_fma_f32 v[48:49], v[24:25], v[44:45], v[48:49]
	v_fmac_f32_e32 v66, v62, v65
	v_add_f32_dpp v34, v34, v34 row_ror:8 row_mask:0xf bank_mask:0xf bound_ctrl:1
	v_pk_fma_f32 v[22:23], v[54:55], v[34:35], v[46:47] op_sel_hi:[1,0,1]
	v_pk_fma_f32 v[24:25], v[56:57], v[34:35], v[48:49] op_sel_hi:[1,0,1]
	ds_write2st64_b32 v41, v36, v66 offset0:28 offset1:29
	s_waitcnt lgkmcnt(4)
	ds_read_b128 v[50:53], v38 offset:49120
	ds_read_b128 v[58:61], v38 offset:49632
	ds_read_b128 v[46:49], v38 offset:48864
	ds_read_b32 v62, v39 offset:49888
	ds_read_b128 v[42:45], v38 offset:48608
	ds_read_b32 v65, v40 offset:50148
	ds_read_b128 v[54:57], v38 offset:49376
	v_pk_mul_f32 v[34:35], v[22:23], v[10:11]
	v_pk_mul_f32 v[36:37], v[22:23], v[18:19]
	v_pk_fma_f32 v[34:35], v[24:25], v[12:13], v[34:35]
	v_pk_fma_f32 v[36:37], v[24:25], v[20:21], v[36:37]
	v_add_f32_e32 v34, v34, v35
	v_add_f32_e32 v36, v36, v37
	v_pk_mul_f32 v[6:7], v[6:7], v[28:29] op_sel_hi:[1,0]
	v_add_f32_dpp v34, v34, v34 row_ror:1 row_mask:0xf bank_mask:0xf bound_ctrl:1
	v_pk_mul_f32 v[8:9], v[8:9], v[28:29] op_sel_hi:[1,0]
	v_add_f32_dpp v36, v36, v36 row_ror:1 row_mask:0xf bank_mask:0xf bound_ctrl:1
	v_add_f32_dpp v34, v34, v34 row_ror:2 row_mask:0xf bank_mask:0xf bound_ctrl:1
	s_waitcnt lgkmcnt(8)
	v_pk_fma_f32 v[6:7], v[22:23], v[2:3], v[6:7]
	v_add_f32_dpp v36, v36, v36 row_ror:2 row_mask:0xf bank_mask:0xf bound_ctrl:1
	v_add_f32_dpp v34, v34, v34 row_ror:4 row_mask:0xf bank_mask:0xf bound_ctrl:1
	v_pk_fma_f32 v[8:9], v[24:25], v[4:5], v[8:9]
	v_fmac_f32_e32 v36, v28, v33
	v_add_f32_dpp v34, v34, v34 row_ror:8 row_mask:0xf bank_mask:0xf bound_ctrl:1
	v_pk_fma_f32 v[22:23], v[14:15], v[34:35], v[6:7] op_sel_hi:[1,0,1]
	v_pk_fma_f32 v[24:25], v[16:17], v[34:35], v[8:9] op_sel_hi:[1,0,1]
	s_waitcnt lgkmcnt(3)
	v_pk_mul_f32 v[34:35], v[22:23], v[50:51]
	v_pk_mul_f32 v[66:67], v[22:23], v[58:59]
	v_pk_fma_f32 v[34:35], v[24:25], v[52:53], v[34:35]
	v_pk_fma_f32 v[66:67], v[24:25], v[60:61], v[66:67]
	v_add_f32_e32 v34, v34, v35
	v_add_f32_e32 v66, v66, v67
	v_pk_mul_f32 v[46:47], v[46:47], v[62:63] op_sel_hi:[1,0]
	v_add_f32_dpp v34, v34, v34 row_ror:1 row_mask:0xf bank_mask:0xf bound_ctrl:1
	v_pk_mul_f32 v[48:49], v[48:49], v[62:63] op_sel_hi:[1,0]
	v_add_f32_dpp v66, v66, v66 row_ror:1 row_mask:0xf bank_mask:0xf bound_ctrl:1
	v_add_f32_dpp v34, v34, v34 row_ror:2 row_mask:0xf bank_mask:0xf bound_ctrl:1
	s_waitcnt lgkmcnt(0)
	v_pk_fma_f32 v[46:47], v[22:23], v[42:43], v[46:47]
	v_add_f32_dpp v66, v66, v66 row_ror:2 row_mask:0xf bank_mask:0xf bound_ctrl:1
	v_add_f32_dpp v34, v34, v34 row_ror:4 row_mask:0xf bank_mask:0xf bound_ctrl:1
	v_pk_fma_f32 v[48:49], v[24:25], v[44:45], v[48:49]
	v_fmac_f32_e32 v66, v62, v65
	v_add_f32_dpp v34, v34, v34 row_ror:8 row_mask:0xf bank_mask:0xf bound_ctrl:1
	v_pk_fma_f32 v[22:23], v[54:55], v[34:35], v[46:47] op_sel_hi:[1,0,1]
	v_pk_fma_f32 v[24:25], v[56:57], v[34:35], v[48:49] op_sel_hi:[1,0,1]
	ds_write2st64_b32 v41, v36, v66 offset0:30 offset1:31
	s_add_i32 s14, s14, 1
	s_cmpk_eq_i32 s14, 0x100
	s_waitcnt lgkmcnt(0)
	s_barrier
	s_cbranch_scc0 .LBB0_1090
	s_setprio 0
	s_mov_b64 s[44:45], 0
